# phase 0 converts only w_in; w_a/w_b/LoRA conversion moved to the idle last round of GEMM1; dt_phase on the workgroups without a twelfth unit
# speedup vs baseline: 1.0341x; 1.0034x over previous
.LBB0_7:
	s_or_b64 exec, exec, s[4:5]
	s_cmp_lt_i32 s50, 1
	s_cselect_b64 s[0:1], -1, 0
	s_cmp_gt_i32 s51, 0
	s_cselect_b64 s[4:5], -1, 0
	s_and_b64 s[8:9], s[0:1], s[4:5]
	s_andn2_b64 vcc, exec, s[8:9]
	v_lshrrev_b32_e32 v179, 6, v178
	s_cbranch_vccnz .LBB0_356
	v_lshl_add_u32 v34, s2, 3, v179
	s_movk_i32 s99, 0x1b10
	s_cmp_eq_u32 s48, 0x100
	s_cselect_b32 s99, 0x1490, s99
	s_mov_b32 s98, 0
.Ltr_early_entry:
	s_mov_b32 s0, s99
	v_mov_b32_e32 v2, 0
	v_cmp_gt_i32_e32 vcc, s0, v34
	v_bfe_u32 v35, v178, 5, 1
	v_and_b32_e32 v33, 31, v178
	v_mov_b32_e32 v1, v2
	v_mov_b32_e32 v4, v2
	v_mov_b32_e32 v3, v2
	v_mov_b32_e32 v6, v2
	v_mov_b32_e32 v5, v2
	v_mov_b32_e32 v8, v2
	v_mov_b32_e32 v7, v2
	v_mov_b32_e32 v10, v2
	v_mov_b32_e32 v9, v2
	v_mov_b32_e32 v12, v2
	v_mov_b32_e32 v11, v2
	v_mov_b32_e32 v14, v2
	v_mov_b32_e32 v13, v2
	v_mov_b32_e32 v16, v2
	v_mov_b32_e32 v15, v2
	v_mov_b32_e32 v18, v2
	v_mov_b32_e32 v17, v2
	v_mov_b32_e32 v20, v2
	v_mov_b32_e32 v19, v2
	v_mov_b32_e32 v22, v2
	v_mov_b32_e32 v21, v2
	v_mov_b32_e32 v24, v2
	v_mov_b32_e32 v23, v2
	v_mov_b32_e32 v26, v2
	v_mov_b32_e32 v25, v2
	v_mov_b32_e32 v28, v2
	v_mov_b32_e32 v27, v2
	v_mov_b32_e32 v30, v2
	v_mov_b32_e32 v29, v2
	v_mov_b32_e32 v32, v2
	v_mov_b32_e32 v31, v2
	s_and_saveexec_b64 s[4:5], vcc
	s_cbranch_execz .LBB0_94
	s_movk_i32 s0, 0x148f
	v_cmp_lt_i32_e32 vcc, s0, v34
	s_and_saveexec_b64 s[0:1], vcc
	s_xor_b64 s[6:7], exec, s[0:1]
	s_cbranch_execz .LBB0_27
	v_subrev_co_u32_e32 v3, vcc, 0x1890, v34
	s_xor_b64 s[0:1], vcc, -1
	s_and_saveexec_b64 s[10:11], s[0:1]
	s_xor_b64 s[10:11], exec, s[10:11]
	s_cbranch_execz .LBB0_24
	s_movk_i32 s0, 0x1a8f
	v_cmp_lt_u32_e32 vcc, s0, v34
	s_and_saveexec_b64 s[0:1], vcc
	s_xor_b64 s[12:13], exec, s[0:1]
	s_cbranch_execz .LBB0_21
	s_movk_i32 s0, 0x1aaf
	v_cmp_lt_u32_e32 vcc, s0, v34
	v_lshlrev_b32_e32 v3, 5, v34
	s_and_saveexec_b64 s[0:1], vcc
	s_xor_b64 s[14:15], exec, s[0:1]
	s_cbranch_execz .LBB0_18
	v_subrev_co_u32_e32 v4, vcc, 0x1ad0, v34
	s_xor_b64 s[0:1], vcc, -1
	s_and_saveexec_b64 s[16:17], s[0:1]
	s_xor_b64 s[16:17], exec, s[16:17]
	s_cbranch_execz .LBB0_15
	s_add_i32 s0, 0, 0x200a8
	v_mov_b32_e32 v1, s0
	ds_read_b64 v[6:7], v1
	v_lshlrev_b32_e32 v1, 1, v4
	v_lshlrev_b32_e32 v2, 5, v4
	v_and_b32_e32 v1, 0x7fffffc0, v1
	v_and_b32_e32 v2, 0x3e0, v2
	s_waitcnt lgkmcnt(0)
	v_readfirstlane_b32 s18, v6
	v_readfirstlane_b32 s19, v7

.LBB0_94:
	s_or_b64 exec, exec, s[4:5]
	s_lshl_b32 s3, s48, 3
	s_add_u32 s10, s46, 0x2e80000
	v_lshlrev_b32_e32 v37, 8, v178
	s_addc_u32 s11, s47, 0
	v_and_b32_e32 v37, 0x3c000, v37
	s_add_u32 s12, s46, 0x1a00000
	v_and_b32_e32 v36, 63, v178
	v_add_u32_e32 v42, 0, v37
	v_lshlrev_b32_e32 v37, 3, v178
	s_addc_u32 s13, s47, 0
	v_lshrrev_b32_e32 v39, 3, v36
	v_and_b32_e32 v38, 56, v37
	s_add_u32 s14, s46, 0x1600000
	v_mul_u32_u24_e32 v40, 0x84, v38
	v_lshlrev_b32_e32 v43, 2, v39
	s_addc_u32 s15, s47, 0
	v_add3_u32 v66, v42, v40, v43
	s_add_u32 s16, s46, 0x100000
	v_mul_u32_u24_e32 v43, 0x84, v35
	v_lshlrev_b32_e32 v40, 2, v33
	v_mov_b32_e32 v41, 0
	v_or_b32_e32 v67, 8, v39
	v_or_b32_e32 v68, 16, v39
	v_or_b32_e32 v69, 24, v39
	s_addc_u32 s17, s47, 0
	v_add3_u32 v70, v42, v43, v40
	s_mov_b64 s[18:19], 0
	s_mov_b32 s38, s99
	s_sub_i32 s39, s99, 1
	s_movk_i32 s40, 0x148f
	s_movk_i32 s41, 0x188f
	s_movk_i32 s42, 0x1a8f
	s_movk_i32 s43, 0x1aaf
	s_movk_i32 s56, 0x1acf
	s_add_i32 s57, 0, 0x200a8
	s_add_i32 s58, 0, 0x200a0
	s_add_i32 s59, 0, 0x20090
	s_add_i32 s60, 0, 0x200d8
	s_add_i32 s61, 0, 0x20078
	s_mov_b32 s62, 0x18e6527b
	s_movk_i32 s63, 0x149
	s_add_i32 s64, 0, 0x20038
	s_movk_i32 s65, 0xa0
	v_mov_b32_e32 v71, 0xfffcaa00
	v_mov_b32_e32 v72, 0xfffcae00
	v_mov_b32_e32 v73, 0x2900
	v_mov_b32_e32 v156, v34
	s_branch .LBB0_98

.LBB0_312:
	s_or_b64 exec, exec, s[18:19]
	s_cmp_eq_u32 s98, 1
	s_cbranch_scc1 .Ltr_ret1
	s_waitcnt vmcnt(0) lgkmcnt(0)
	v_lshl_add_u32 v6, s2, 9, v178
	s_movk_i32 s0, 0x7000
	s_lshl_b32 s6, s48, 9
	v_cmp_gt_i32_e32 vcc, s0, v6
	s_and_saveexec_b64 s[4:5], vcc
	s_cbranch_execz .LBB0_315
	v_ashrrev_i32_e32 v7, 31, v6
	v_lshl_add_u64 v[2:3], v[6:7], 4, s[46:47]
	s_mov_b64 s[0:1], 0x1590000
	v_lshl_add_u64 v[8:9], v[2:3], 0, s[0:1]
	s_ashr_i32 s7, s6, 31
	v_mov_b32_e32 v2, 0
	s_lshl_b64 s[12:13], s[6:7], 4
	s_mov_b64 s[14:15], 0
	v_mov_b32_e32 v3, v2
	v_mov_b32_e32 v4, v2
	v_mov_b32_e32 v5, v2
	s_movk_i32 s0, 0x6fff
	v_mov_b32_e32 v1, v6

.LBB0_559:
	s_sub_i32 s0, s48, s2
	s_sub_i32 s0, s0, 1
	v_lshl_add_u32 v24, s0, 3, v179
	s_movk_i32 s0, 0x440
	v_cmp_gt_i32_e32 vcc, s0, v24
	s_waitcnt lgkmcnt(0)
	v_readfirstlane_b32 s4, v2
	v_readfirstlane_b32 s5, v3
	s_and_saveexec_b64 s[6:7], vcc
	s_cbranch_execz .LBB0_564
	v_mov_b32_e32 v11, 0
	v_bfe_u32 v4, v178, 4, 2
	v_lshlrev_b32_e32 v2, 11, v1
	v_mov_b32_e32 v3, v11
	v_lshlrev_b32_e32 v10, 4, v4
	v_lshl_add_u64 v[2:3], s[46:47], 0, v[2:3]
	v_lshl_add_u64 v[2:3], v[2:3], 0, v[10:11]
	s_mov_b64 s[0:1], 0x1580000
	v_lshl_add_u64 v[12:13], s[28:29], 0, v[10:11]
	v_lshl_add_u64 v[14:15], v[2:3], 0, s[0:1]
	s_mov_b64 s[0:1], 0x1588000
	v_lshlrev_b32_e32 v10, 2, v1
	s_lshl_b32 s3, s48, 3
	v_lshl_add_u64 v[16:17], v[2:3], 0, s[0:1]
	v_lshlrev_b32_e32 v25, 2, v4
	v_lshl_add_u64 v[18:19], s[26:27], 0, v[10:11]
	v_lshl_add_u64 v[20:21], s[4:5], 0, v[10:11]
	s_mov_b64 s[8:9], 0
	s_mov_b32 s11, 0
	s_mov_b32 s60, 0x41a00000
	s_mov_b32 s61, 0x800000
	s_mov_b32 s62, 0x3f317217
	s_mov_b32 s63, 0x7f800000
	s_movk_i32 s64, 0x43f
	v_mov_b32_e32 v10, 0x41b17218

.LBB0_564:
	s_or_b64 exec, exec, s[6:7]
	s_cmp_eq_u32 s48, 0x100
	s_cbranch_scc0 .Ltr_skip1
	s_cmp_lt_u32 s2, 40
	s_cbranch_scc1 .Ltr_skip1
	s_mov_b64 s[100:101], s[20:21]
	s_sub_i32 s0, s2, 40
	v_lshl_add_u32 v34, s0, 3, v179
	v_add_u32_e32 v34, 0x1490, v34
	s_movk_i32 s99, 0x1b10
	s_mov_b32 s98, 1
	s_branch .Ltr_early_entry
.Ltr_ret1:
	s_mov_b64 s[20:21], s[100:101]
.Ltr_skip1:
.LBB0_565:
	s_cmp_gt_i32 s51, 2
	s_cselect_b64 s[4:5], -1, 0
	s_and_b64 s[0:1], s[20:21], s[4:5]
	s_andn2_b64 vcc, exec, s[0:1]
	s_cbranch_vccnz .LBB0_633
	s_cmp_gt_i32 s50, -1
	s_mov_b64 s[6:7], -1
	s_cbranch_scc0 .LBB0_620
	s_waitcnt vmcnt(0)
	s_waitcnt vmcnt(0)
	s_barrier
	s_and_saveexec_b64 s[6:7], s[84:85]
	s_cbranch_execz .LBB0_619
	s_add_i32 s0, 0, 0x20800
	v_mov_b32_e32 v1, s0
	s_waitcnt vmcnt(0) expcnt(0) lgkmcnt(0)
	ds_read_b32 v3, v1
	s_add_i32 s0, 0, 0x20804
	v_mov_b32_e32 v1, s0
	ds_read_b32 v1, v1
	s_waitcnt lgkmcnt(1)
	v_cmp_ne_u32_e32 vcc, 0, v3
	s_cbranch_vccnz .LBB0_583
	s_add_u32 s8, s46, 0x80200
	s_addc_u32 s9, s47, 0
	s_add_u32 s10, s46, 0x80400
	s_addc_u32 s11, s47, 0
	s_add_u32 s12, s46, 0x80500
	s_addc_u32 s13, s47, 0
	s_add_u32 s14, s46, 0x80600
	s_addc_u32 s15, s47, 0
	s_add_u32 s16, s46, 0x80700
	s_addc_u32 s17, s47, 0
	s_add_u32 s18, s46, 0x80800
	s_addc_u32 s19, s47, 0
	s_add_u32 s20, s46, 0x80900
	s_addc_u32 s21, s47, 0
	s_add_u32 s22, s46, 0x80a00
	s_addc_u32 s23, s47, 0
	s_add_u32 s24, s46, 0x80b00
	s_addc_u32 s25, s47, 0
	s_add_u32 s26, s46, 0x80c00
	s_addc_u32 s27, s47, 0
	s_add_u32 s28, s46, 0x80d00
	s_addc_u32 s29, s47, 0
	s_add_u32 s30, s46, 0x80e00
	s_addc_u32 s31, s47, 0
	s_add_u32 s34, s46, 0x80f00
	s_addc_u32 s35, s47, 0
	s_add_u32 s36, s46, 0x81000
	s_addc_u32 s37, s47, 0
	s_add_u32 s38, s46, 0x81100
	s_addc_u32 s39, s47, 0
	s_add_u32 s40, s46, 0x81200
	v_readlane_b32 s0, v249, 0
	s_addc_u32 s41, s47, 0
	s_mul_i32 s0, s49, s0
	s_add_u32 s42, s46, 0x81300
	s_mul_i32 s0, s0, s48
	s_addc_u32 s43, s47, 0
	s_mov_b32 s1, 1
	v_mov_b32_e32 v17, 0
	s_branch .LBB0_571
